# kvloc_pair: all 16 K/V chunk loads issued up front with counted waits instead of eight serial load-wait-store rounds; conv_item: vmcnt(0) between its two load batches removed
# speedup vs baseline: 1.0361x; 1.0024x over previous
.LBB0_454:
	s_and_b64 vcc, exec, s[0:1]
	s_cbranch_vccz .LBB0_456
	v_mov_b32_e32 v8, v226
	s_lshl_b32 s0, s30, 1
	v_readfirstlane_b32 s21, v8
	s_ashr_i32 s31, s21, 8
	s_add_i32 s0, s0, s31
	s_addk_i32 s0, 0xfd00
	s_bfe_u32 s20, s0, 0x20004
	v_cvt_f32_ubyte0_e32 v0, s20
	v_sub_f32_e32 v0, 0xc0a00000, v0
	v_cmp_gt_f32_e32 vcc, s3, v0
	s_ashr_i32 s34, s0, 6
	s_and_b32 s1, s0, 15
	v_cndmask_b32_e32 v1, 0, v233, vcc
	v_add_f32_e32 v0, v0, v1
	v_exp_f32_e32 v0, v0
	s_and_b64 s[22:23], vcc, exec
	s_cselect_b32 s22, 0xffffffc0, 0
	s_ashr_i32 s35, s34, 31
	v_ldexp_f32 v0, v0, s22
	s_mul_i32 s31, s31, 0x11000
	s_lshl_b64 s[34:35], s[34:35], 11
	s_lshl_b32 s23, s1, 7
	v_sub_f32_e32 v0, 1.0, v0
	s_add_i32 s22, s31, 0
	s_or_b32 s23, s34, s23
	s_lshl_b32 s31, s20, 8
	v_log_f32_e32 v9, v0
	s_add_u32 s40, s50, s31
	v_lshlrev_b32_e32 v0, 4, v8
	v_bfe_u32 v11, v8, 4, 4
	s_addc_u32 s41, s51, 0
	v_and_b32_e32 v208, 0xf0, v0
	v_or_b32_e32 v2, s23, v11
	v_mov_b32_e32 v3, s35
	v_lshl_add_u64 v[0:1], s[40:41], 0, v[208:209]
	v_lshlrev_b64 v[6:7], 10, v[2:3]
	v_lshl_add_u64 v[12:13], v[0:1], 0, v[6:7]
	s_add_u32 s40, s90, s31
	s_addc_u32 s41, s91, 0
	v_lshl_add_u64 v[4:5], s[40:41], 0, v[208:209]
	v_lshl_add_u64 v[6:7], v[4:5], 0, v[6:7]
	s_mov_b32 s98, 0x4000
	s_mov_b32 s99, 0
	global_load_dwordx4 v[24:27], v[12:13], off
	global_load_dwordx4 v[28:31], v[6:7], off
	v_lshl_add_u64 v[12:13], v[12:13], 0, s[98:99]
	v_lshl_add_u64 v[6:7], v[6:7], 0, s[98:99]
	global_load_dwordx4 v[32:35], v[12:13], off
	global_load_dwordx4 v[36:39], v[6:7], off
	v_lshl_add_u64 v[12:13], v[12:13], 0, s[98:99]
	v_lshl_add_u64 v[6:7], v[6:7], 0, s[98:99]
	global_load_dwordx4 v[40:43], v[12:13], off
	global_load_dwordx4 v[44:47], v[6:7], off
	v_lshl_add_u64 v[12:13], v[12:13], 0, s[98:99]
	v_lshl_add_u64 v[6:7], v[6:7], 0, s[98:99]
	global_load_dwordx4 v[48:51], v[12:13], off
	global_load_dwordx4 v[52:55], v[6:7], off
	v_lshl_add_u64 v[12:13], v[12:13], 0, s[98:99]
	v_lshl_add_u64 v[6:7], v[6:7], 0, s[98:99]
	global_load_dwordx4 v[56:59], v[12:13], off
	global_load_dwordx4 v[60:63], v[6:7], off
	v_lshl_add_u64 v[12:13], v[12:13], 0, s[98:99]
	v_lshl_add_u64 v[6:7], v[6:7], 0, s[98:99]
	global_load_dwordx4 v[64:67], v[12:13], off
	global_load_dwordx4 v[68:71], v[6:7], off
	v_lshl_add_u64 v[12:13], v[12:13], 0, s[98:99]
	v_lshl_add_u64 v[6:7], v[6:7], 0, s[98:99]
	global_load_dwordx4 v[72:75], v[12:13], off
	global_load_dwordx4 v[76:79], v[6:7], off
	v_lshl_add_u64 v[12:13], v[12:13], 0, s[98:99]
	v_lshl_add_u64 v[6:7], v[6:7], 0, s[98:99]
	global_load_dwordx4 v[80:83], v[12:13], off
	global_load_dwordx4 v[84:87], v[6:7], off
	s_bfe_u32 s21, s21, 0x20006
	s_andn2_b32 s0, s0, 63
	s_lshl_b32 s20, s20, 4
	s_or_b32 s0, s20, s0
	s_or_b32 s0, s0, s1
	s_ashr_i32 s1, s0, 31
	s_lshl_b64 s[0:1], s[0:1], 15
	s_add_u32 s0, s56, s0
	s_addc_u32 s1, s57, s1
	s_movk_i32 s23, 0x4f
	v_lshrrev_b32_e32 v10, 4, v8
	v_mul_u32_u24_e32 v16, 0x110, v11
	v_add3_u32 v11, s22, v208, v16
	s_movk_i32 s100, 0x7f
	v_bitop3_b32 v16, v10, s100, 15 bitop3:0x6c
	v_cvt_f32_ubyte0_e32 v16, v16
	v_mul_f32_e32 v17, v9, v16
	v_cmp_gt_f32_e32 vcc, s3, v17
	s_nop 0
	v_cndmask_b32_e32 v17, 0, v233, vcc
	v_fmac_f32_e32 v17, v9, v16
	v_exp_f32_e32 v16, v17
	v_cndmask_b32_e32 v17, 0, v234, vcc
	s_nop 0
	v_ldexp_f32 v16, v16, v17
	s_waitcnt vmcnt(15)
	v_lshlrev_b32_e32 v20, 16, v24
	v_and_b32_e32 v21, 0xffff0000, v24
	v_pk_mul_f32 v[20:21], v[16:17], v[20:21] op_sel_hi:[0,1]
	v_cvt_pk_bf16_f32 v24, v20, v21
	v_lshlrev_b32_e32 v20, 16, v25
	v_and_b32_e32 v21, 0xffff0000, v25
	v_pk_mul_f32 v[20:21], v[16:17], v[20:21] op_sel_hi:[0,1]
	v_cvt_pk_bf16_f32 v25, v20, v21
	v_lshlrev_b32_e32 v20, 16, v26
	v_and_b32_e32 v21, 0xffff0000, v26
	v_pk_mul_f32 v[20:21], v[16:17], v[20:21] op_sel_hi:[0,1]
	v_cvt_pk_bf16_f32 v26, v20, v21
	v_lshlrev_b32_e32 v20, 16, v27
	v_and_b32_e32 v21, 0xffff0000, v27
	v_pk_mul_f32 v[20:21], v[16:17], v[20:21] op_sel_hi:[0,1]
	v_cvt_pk_bf16_f32 v27, v20, v21
	ds_write_b128 v11, v[24:27]
	s_waitcnt vmcnt(14)
	ds_write_b128 v11, v[28:31] offset:34816
	s_movk_i32 s100, 0x6f
	v_bitop3_b32 v16, v10, s100, 15 bitop3:0x6c
	v_cvt_f32_ubyte0_e32 v16, v16
	v_mul_f32_e32 v17, v9, v16
	v_cmp_gt_f32_e32 vcc, s3, v17
	s_nop 0
	v_cndmask_b32_e32 v17, 0, v233, vcc
	v_fmac_f32_e32 v17, v9, v16
	v_exp_f32_e32 v16, v17
	v_cndmask_b32_e32 v17, 0, v234, vcc
	s_nop 0
	v_ldexp_f32 v16, v16, v17
	s_waitcnt vmcnt(13)
	v_lshlrev_b32_e32 v20, 16, v32
	v_and_b32_e32 v21, 0xffff0000, v32
	v_pk_mul_f32 v[20:21], v[16:17], v[20:21] op_sel_hi:[0,1]
	v_cvt_pk_bf16_f32 v32, v20, v21
	v_lshlrev_b32_e32 v20, 16, v33
	v_and_b32_e32 v21, 0xffff0000, v33
	v_pk_mul_f32 v[20:21], v[16:17], v[20:21] op_sel_hi:[0,1]
	v_cvt_pk_bf16_f32 v33, v20, v21
	v_lshlrev_b32_e32 v20, 16, v34
	v_and_b32_e32 v21, 0xffff0000, v34
	v_pk_mul_f32 v[20:21], v[16:17], v[20:21] op_sel_hi:[0,1]
	v_cvt_pk_bf16_f32 v34, v20, v21
	v_lshlrev_b32_e32 v20, 16, v35
	v_and_b32_e32 v21, 0xffff0000, v35
	v_pk_mul_f32 v[20:21], v[16:17], v[20:21] op_sel_hi:[0,1]
	v_cvt_pk_bf16_f32 v35, v20, v21
	ds_write_b128 v11, v[32:35] offset:4352
	s_waitcnt vmcnt(12)
	ds_write_b128 v11, v[36:39] offset:39168
	s_movk_i32 s100, 0x5f
	v_bitop3_b32 v16, v10, s100, 15 bitop3:0x6c
	v_cvt_f32_ubyte0_e32 v16, v16
	v_mul_f32_e32 v17, v9, v16
	v_cmp_gt_f32_e32 vcc, s3, v17
	s_nop 0
	v_cndmask_b32_e32 v17, 0, v233, vcc
	v_fmac_f32_e32 v17, v9, v16
	v_exp_f32_e32 v16, v17
	v_cndmask_b32_e32 v17, 0, v234, vcc
	s_nop 0
	v_ldexp_f32 v16, v16, v17
	s_waitcnt vmcnt(11)
	v_lshlrev_b32_e32 v20, 16, v40
	v_and_b32_e32 v21, 0xffff0000, v40
	v_pk_mul_f32 v[20:21], v[16:17], v[20:21] op_sel_hi:[0,1]
	v_cvt_pk_bf16_f32 v40, v20, v21
	v_lshlrev_b32_e32 v20, 16, v41
	v_and_b32_e32 v21, 0xffff0000, v41
	v_pk_mul_f32 v[20:21], v[16:17], v[20:21] op_sel_hi:[0,1]
	v_cvt_pk_bf16_f32 v41, v20, v21
	v_lshlrev_b32_e32 v20, 16, v42
	v_and_b32_e32 v21, 0xffff0000, v42
	v_pk_mul_f32 v[20:21], v[16:17], v[20:21] op_sel_hi:[0,1]
	v_cvt_pk_bf16_f32 v42, v20, v21
	v_lshlrev_b32_e32 v20, 16, v43
	v_and_b32_e32 v21, 0xffff0000, v43
	v_pk_mul_f32 v[20:21], v[16:17], v[20:21] op_sel_hi:[0,1]
	v_cvt_pk_bf16_f32 v43, v20, v21
	ds_write_b128 v11, v[40:43] offset:8704
	s_waitcnt vmcnt(10)
	ds_write_b128 v11, v[44:47] offset:43520
	s_movk_i32 s100, 0x4f
	v_bitop3_b32 v16, v10, s100, 15 bitop3:0x6c
	v_cvt_f32_ubyte0_e32 v16, v16
	v_mul_f32_e32 v17, v9, v16
	v_cmp_gt_f32_e32 vcc, s3, v17
	s_nop 0
	v_cndmask_b32_e32 v17, 0, v233, vcc
	v_fmac_f32_e32 v17, v9, v16
	v_exp_f32_e32 v16, v17
	v_cndmask_b32_e32 v17, 0, v234, vcc
	s_nop 0
	v_ldexp_f32 v16, v16, v17
	s_waitcnt vmcnt(9)
	v_lshlrev_b32_e32 v20, 16, v48
	v_and_b32_e32 v21, 0xffff0000, v48
	v_pk_mul_f32 v[20:21], v[16:17], v[20:21] op_sel_hi:[0,1]
	v_cvt_pk_bf16_f32 v48, v20, v21
	v_lshlrev_b32_e32 v20, 16, v49
	v_and_b32_e32 v21, 0xffff0000, v49
	v_pk_mul_f32 v[20:21], v[16:17], v[20:21] op_sel_hi:[0,1]
	v_cvt_pk_bf16_f32 v49, v20, v21
	v_lshlrev_b32_e32 v20, 16, v50
	v_and_b32_e32 v21, 0xffff0000, v50
	v_pk_mul_f32 v[20:21], v[16:17], v[20:21] op_sel_hi:[0,1]
	v_cvt_pk_bf16_f32 v50, v20, v21
	v_lshlrev_b32_e32 v20, 16, v51
	v_and_b32_e32 v21, 0xffff0000, v51
	v_pk_mul_f32 v[20:21], v[16:17], v[20:21] op_sel_hi:[0,1]
	v_cvt_pk_bf16_f32 v51, v20, v21
	ds_write_b128 v11, v[48:51] offset:13056
	s_waitcnt vmcnt(8)
	ds_write_b128 v11, v[52:55] offset:47872
	v_bitop3_b32 v16, v10, 63, 15 bitop3:0x6c
	v_cvt_f32_ubyte0_e32 v16, v16
	v_mul_f32_e32 v17, v9, v16
	v_cmp_gt_f32_e32 vcc, s3, v17
	s_nop 0
	v_cndmask_b32_e32 v17, 0, v233, vcc
	v_fmac_f32_e32 v17, v9, v16
	v_exp_f32_e32 v16, v17
	v_cndmask_b32_e32 v17, 0, v234, vcc
	s_nop 0
	v_ldexp_f32 v16, v16, v17
	s_waitcnt vmcnt(7)
	v_lshlrev_b32_e32 v20, 16, v56
	v_and_b32_e32 v21, 0xffff0000, v56
	v_pk_mul_f32 v[20:21], v[16:17], v[20:21] op_sel_hi:[0,1]
	v_cvt_pk_bf16_f32 v56, v20, v21
	v_lshlrev_b32_e32 v20, 16, v57
	v_and_b32_e32 v21, 0xffff0000, v57
	v_pk_mul_f32 v[20:21], v[16:17], v[20:21] op_sel_hi:[0,1]
	v_cvt_pk_bf16_f32 v57, v20, v21
	v_lshlrev_b32_e32 v20, 16, v58
	v_and_b32_e32 v21, 0xffff0000, v58
	v_pk_mul_f32 v[20:21], v[16:17], v[20:21] op_sel_hi:[0,1]
	v_cvt_pk_bf16_f32 v58, v20, v21
	v_lshlrev_b32_e32 v20, 16, v59
	v_and_b32_e32 v21, 0xffff0000, v59
	v_pk_mul_f32 v[20:21], v[16:17], v[20:21] op_sel_hi:[0,1]
	v_cvt_pk_bf16_f32 v59, v20, v21
	ds_write_b128 v11, v[56:59] offset:17408
	s_waitcnt vmcnt(6)
	ds_write_b128 v11, v[60:63] offset:52224
	v_bitop3_b32 v16, v10, 47, 15 bitop3:0x6c
	v_cvt_f32_ubyte0_e32 v16, v16
	v_mul_f32_e32 v17, v9, v16
	v_cmp_gt_f32_e32 vcc, s3, v17
	s_nop 0
	v_cndmask_b32_e32 v17, 0, v233, vcc
	v_fmac_f32_e32 v17, v9, v16
	v_exp_f32_e32 v16, v17
	v_cndmask_b32_e32 v17, 0, v234, vcc
	s_nop 0
	v_ldexp_f32 v16, v16, v17
	s_waitcnt vmcnt(5)
	v_lshlrev_b32_e32 v20, 16, v64
	v_and_b32_e32 v21, 0xffff0000, v64
	v_pk_mul_f32 v[20:21], v[16:17], v[20:21] op_sel_hi:[0,1]
	v_cvt_pk_bf16_f32 v64, v20, v21
	v_lshlrev_b32_e32 v20, 16, v65
	v_and_b32_e32 v21, 0xffff0000, v65
	v_pk_mul_f32 v[20:21], v[16:17], v[20:21] op_sel_hi:[0,1]
	v_cvt_pk_bf16_f32 v65, v20, v21
	v_lshlrev_b32_e32 v20, 16, v66
	v_and_b32_e32 v21, 0xffff0000, v66
	v_pk_mul_f32 v[20:21], v[16:17], v[20:21] op_sel_hi:[0,1]
	v_cvt_pk_bf16_f32 v66, v20, v21
	v_lshlrev_b32_e32 v20, 16, v67
	v_and_b32_e32 v21, 0xffff0000, v67
	v_pk_mul_f32 v[20:21], v[16:17], v[20:21] op_sel_hi:[0,1]
	v_cvt_pk_bf16_f32 v67, v20, v21
	ds_write_b128 v11, v[64:67] offset:21760
	s_waitcnt vmcnt(4)
	ds_write_b128 v11, v[68:71] offset:56576
	v_bitop3_b32 v16, v10, 31, 15 bitop3:0x6c
	v_cvt_f32_ubyte0_e32 v16, v16
	v_mul_f32_e32 v17, v9, v16
	v_cmp_gt_f32_e32 vcc, s3, v17
	s_nop 0
	v_cndmask_b32_e32 v17, 0, v233, vcc
	v_fmac_f32_e32 v17, v9, v16
	v_exp_f32_e32 v16, v17
	v_cndmask_b32_e32 v17, 0, v234, vcc
	s_nop 0
	v_ldexp_f32 v16, v16, v17
	s_waitcnt vmcnt(3)
	v_lshlrev_b32_e32 v20, 16, v72
	v_and_b32_e32 v21, 0xffff0000, v72
	v_pk_mul_f32 v[20:21], v[16:17], v[20:21] op_sel_hi:[0,1]
	v_cvt_pk_bf16_f32 v72, v20, v21
	v_lshlrev_b32_e32 v20, 16, v73
	v_and_b32_e32 v21, 0xffff0000, v73
	v_pk_mul_f32 v[20:21], v[16:17], v[20:21] op_sel_hi:[0,1]
	v_cvt_pk_bf16_f32 v73, v20, v21
	v_lshlrev_b32_e32 v20, 16, v74
	v_and_b32_e32 v21, 0xffff0000, v74
	v_pk_mul_f32 v[20:21], v[16:17], v[20:21] op_sel_hi:[0,1]
	v_cvt_pk_bf16_f32 v74, v20, v21
	v_lshlrev_b32_e32 v20, 16, v75
	v_and_b32_e32 v21, 0xffff0000, v75
	v_pk_mul_f32 v[20:21], v[16:17], v[20:21] op_sel_hi:[0,1]
	v_cvt_pk_bf16_f32 v75, v20, v21
	ds_write_b128 v11, v[72:75] offset:26112
	s_waitcnt vmcnt(2)
	ds_write_b128 v11, v[76:79] offset:60928
	v_bitop3_b32 v16, v10, 15, 15 bitop3:0x6c
	v_cvt_f32_ubyte0_e32 v16, v16
	v_mul_f32_e32 v17, v9, v16
	v_cmp_gt_f32_e32 vcc, s3, v17
	s_nop 0
	v_cndmask_b32_e32 v17, 0, v233, vcc
	v_fmac_f32_e32 v17, v9, v16
	v_exp_f32_e32 v16, v17
	v_cndmask_b32_e32 v17, 0, v234, vcc
	s_nop 0
	v_ldexp_f32 v16, v16, v17
	s_waitcnt vmcnt(1)
	v_lshlrev_b32_e32 v20, 16, v80
	v_and_b32_e32 v21, 0xffff0000, v80
	v_pk_mul_f32 v[20:21], v[16:17], v[20:21] op_sel_hi:[0,1]
	v_cvt_pk_bf16_f32 v80, v20, v21
	v_lshlrev_b32_e32 v20, 16, v81
	v_and_b32_e32 v21, 0xffff0000, v81
	v_pk_mul_f32 v[20:21], v[16:17], v[20:21] op_sel_hi:[0,1]
	v_cvt_pk_bf16_f32 v81, v20, v21
	v_lshlrev_b32_e32 v20, 16, v82
	v_and_b32_e32 v21, 0xffff0000, v82
	v_pk_mul_f32 v[20:21], v[16:17], v[20:21] op_sel_hi:[0,1]
	v_cvt_pk_bf16_f32 v82, v20, v21
	v_lshlrev_b32_e32 v20, 16, v83
	v_and_b32_e32 v21, 0xffff0000, v83
	v_pk_mul_f32 v[20:21], v[16:17], v[20:21] op_sel_hi:[0,1]
	v_cvt_pk_bf16_f32 v83, v20, v21
	ds_write_b128 v11, v[80:83] offset:30464
	s_waitcnt vmcnt(0)
	ds_write_b128 v11, v[84:87] offset:65280
	v_lshrrev_b32_e32 v0, 1, v8
	v_and_b32_e32 v0, 24, v0
	v_lshrrev_b32_e32 v1, 2, v8
	v_lshlrev_b32_e32 v2, 3, v8
	v_and_b32_e32 v3, 24, v2
	v_and_or_b32 v1, v1, 3, v0
	v_mov_b32_e32 v4, s22
	v_lshl_or_b32 v2, s21, 6, v3
	v_mad_u32_u24 v1, v1, s71, v4
	v_add_u32_e32 v2, v1, v2
	v_add_u32_e32 v1, v1, v3
	s_waitcnt lgkmcnt(0)
	s_barrier
	ds_read_b64_tr_b16 v[6:7], v2 offset:1088
	ds_read_b64_tr_b16 v[4:5], v2
	ds_read_b64_tr_b16 v[10:11], v2 offset:32
	ds_read_b64_tr_b16 v[12:13], v2 offset:1120
	ds_read_b64_tr_b16 v[16:17], v1 offset:35904
	ds_read_b64_tr_b16 v[14:15], v1 offset:34816
	ds_read_b64_tr_b16 v[18:19], v1 offset:34848
	ds_read_b64_tr_b16 v[20:21], v1 offset:35936
	ds_read_b64_tr_b16 v[30:31], v1 offset:34880
	ds_read_b64_tr_b16 v[32:33], v1 offset:35968
	ds_read_b64_tr_b16 v[38:39], v1 offset:34912
	ds_read_b64_tr_b16 v[40:41], v1 offset:36000
	ds_read_b64_tr_b16 v[46:47], v1 offset:34944
	ds_read_b64_tr_b16 v[48:49], v1 offset:36032
	ds_read_b64_tr_b16 v[54:55], v1 offset:34976
	ds_read_b64_tr_b16 v[56:57], v1 offset:36064
	ds_read_b64_tr_b16 v[62:63], v1 offset:35008
	ds_read_b64_tr_b16 v[64:65], v1 offset:36096
	ds_read_b64_tr_b16 v[70:71], v1 offset:35040
	ds_read_b64_tr_b16 v[72:73], v1 offset:36128
	s_waitcnt lgkmcnt(14)
	v_mfma_f32_16x16x32_bf16 v[22:25], v[14:17], v[4:7], 0
	v_mfma_f32_16x16x32_bf16 v[14:17], v[14:17], v[10:13], 0
	s_waitcnt lgkmcnt(12)
	v_mfma_f32_16x16x32_bf16 v[26:29], v[18:21], v[4:7], 0
	v_mfma_f32_16x16x32_bf16 v[18:21], v[18:21], v[10:13], 0
	s_waitcnt lgkmcnt(10)
	v_mfma_f32_16x16x32_bf16 v[34:37], v[30:33], v[4:7], 0
	v_mfma_f32_16x16x32_bf16 v[30:33], v[30:33], v[10:13], 0
	s_waitcnt lgkmcnt(8)
	v_mfma_f32_16x16x32_bf16 v[42:45], v[38:41], v[4:7], 0
	v_mfma_f32_16x16x32_bf16 v[38:41], v[38:41], v[10:13], 0
	s_waitcnt lgkmcnt(6)
	v_mfma_f32_16x16x32_bf16 v[50:53], v[46:49], v[4:7], 0
	v_mfma_f32_16x16x32_bf16 v[46:49], v[46:49], v[10:13], 0
	s_waitcnt lgkmcnt(4)
	v_mfma_f32_16x16x32_bf16 v[58:61], v[54:57], v[4:7], 0
	v_mfma_f32_16x16x32_bf16 v[54:57], v[54:57], v[10:13], 0
	s_waitcnt lgkmcnt(2)
	v_mfma_f32_16x16x32_bf16 v[66:69], v[62:65], v[4:7], 0
	v_mfma_f32_16x16x32_bf16 v[62:65], v[62:65], v[10:13], 0
	s_waitcnt lgkmcnt(0)
	v_mfma_f32_16x16x32_bf16 v[4:7], v[70:73], v[4:7], 0
	v_mfma_f32_16x16x32_bf16 v[10:13], v[70:73], v[10:13], 0
	ds_read_b64_tr_b16 v[70:71], v2 offset:8704
	ds_read_b64_tr_b16 v[72:73], v2 offset:9792
	ds_read_b64_tr_b16 v[74:75], v2 offset:8736
	ds_read_b64_tr_b16 v[76:77], v2 offset:9824
	ds_read_b64_tr_b16 v[78:79], v1 offset:43520
	ds_read_b64_tr_b16 v[80:81], v1 offset:44608
	s_waitcnt lgkmcnt(0)
	v_mfma_f32_16x16x32_bf16 v[22:25], v[78:81], v[70:73], v[22:25]
	v_mfma_f32_16x16x32_bf16 v[14:17], v[78:81], v[74:77], v[14:17]
	ds_read_b64_tr_b16 v[78:79], v1 offset:43552
	ds_read_b64_tr_b16 v[80:81], v1 offset:44640
	s_waitcnt lgkmcnt(0)
	v_mfma_f32_16x16x32_bf16 v[26:29], v[78:81], v[70:73], v[26:29]
	v_mfma_f32_16x16x32_bf16 v[18:21], v[78:81], v[74:77], v[18:21]
	ds_read_b64_tr_b16 v[78:79], v1 offset:43584
	ds_read_b64_tr_b16 v[80:81], v1 offset:44672
	s_waitcnt lgkmcnt(0)
	v_mfma_f32_16x16x32_bf16 v[34:37], v[78:81], v[70:73], v[34:37]
	v_mfma_f32_16x16x32_bf16 v[30:33], v[78:81], v[74:77], v[30:33]
	ds_read_b64_tr_b16 v[78:79], v1 offset:43616
	ds_read_b64_tr_b16 v[80:81], v1 offset:44704
	s_waitcnt lgkmcnt(0)
	v_mfma_f32_16x16x32_bf16 v[42:45], v[78:81], v[70:73], v[42:45]
	v_mfma_f32_16x16x32_bf16 v[38:41], v[78:81], v[74:77], v[38:41]
	ds_read_b64_tr_b16 v[78:79], v1 offset:43648
	ds_read_b64_tr_b16 v[80:81], v1 offset:44736
	s_waitcnt lgkmcnt(0)
	v_mfma_f32_16x16x32_bf16 v[50:53], v[78:81], v[70:73], v[50:53]
	v_mfma_f32_16x16x32_bf16 v[46:49], v[78:81], v[74:77], v[46:49]
	ds_read_b64_tr_b16 v[78:79], v1 offset:43680
	ds_read_b64_tr_b16 v[80:81], v1 offset:44768
	s_waitcnt lgkmcnt(0)
	v_mfma_f32_16x16x32_bf16 v[58:61], v[78:81], v[70:73], v[58:61]
	v_mfma_f32_16x16x32_bf16 v[54:57], v[78:81], v[74:77], v[54:57]
	ds_read_b64_tr_b16 v[78:79], v1 offset:43712
	ds_read_b64_tr_b16 v[80:81], v1 offset:44800
	s_waitcnt lgkmcnt(0)
	v_mfma_f32_16x16x32_bf16 v[66:69], v[78:81], v[70:73], v[66:69]
	v_mfma_f32_16x16x32_bf16 v[62:65], v[78:81], v[74:77], v[62:65]
	ds_read_b64_tr_b16 v[78:79], v1 offset:43744
	ds_read_b64_tr_b16 v[80:81], v1 offset:44832
	s_waitcnt lgkmcnt(0)
	v_mfma_f32_16x16x32_bf16 v[4:7], v[78:81], v[70:73], v[4:7]
	v_mfma_f32_16x16x32_bf16 v[10:13], v[78:81], v[74:77], v[10:13]
	ds_read_b64_tr_b16 v[70:71], v2 offset:17408
	ds_read_b64_tr_b16 v[72:73], v2 offset:18496
	ds_read_b64_tr_b16 v[74:75], v2 offset:17440
	ds_read_b64_tr_b16 v[76:77], v2 offset:18528
	ds_read_b64_tr_b16 v[78:79], v1 offset:52224
	ds_read_b64_tr_b16 v[80:81], v1 offset:53312
	s_waitcnt lgkmcnt(0)
	v_mfma_f32_16x16x32_bf16 v[22:25], v[78:81], v[70:73], v[22:25]
	v_mfma_f32_16x16x32_bf16 v[14:17], v[78:81], v[74:77], v[14:17]
	ds_read_b64_tr_b16 v[78:79], v1 offset:52256
	ds_read_b64_tr_b16 v[80:81], v1 offset:53344
	s_waitcnt lgkmcnt(0)
	v_mfma_f32_16x16x32_bf16 v[26:29], v[78:81], v[70:73], v[26:29]
	v_mfma_f32_16x16x32_bf16 v[18:21], v[78:81], v[74:77], v[18:21]
	ds_read_b64_tr_b16 v[78:79], v1 offset:52288
	ds_read_b64_tr_b16 v[80:81], v1 offset:53376
	s_waitcnt lgkmcnt(0)
	v_mfma_f32_16x16x32_bf16 v[34:37], v[78:81], v[70:73], v[34:37]
	v_mfma_f32_16x16x32_bf16 v[30:33], v[78:81], v[74:77], v[30:33]
	ds_read_b64_tr_b16 v[78:79], v1 offset:52320
	ds_read_b64_tr_b16 v[80:81], v1 offset:53408
	s_waitcnt lgkmcnt(0)
	v_mfma_f32_16x16x32_bf16 v[42:45], v[78:81], v[70:73], v[42:45]
	v_mfma_f32_16x16x32_bf16 v[38:41], v[78:81], v[74:77], v[38:41]
	ds_read_b64_tr_b16 v[78:79], v1 offset:52352
	ds_read_b64_tr_b16 v[80:81], v1 offset:53440
	s_waitcnt lgkmcnt(0)
	v_mfma_f32_16x16x32_bf16 v[50:53], v[78:81], v[70:73], v[50:53]
	v_mfma_f32_16x16x32_bf16 v[46:49], v[78:81], v[74:77], v[46:49]
	ds_read_b64_tr_b16 v[78:79], v1 offset:52384
	ds_read_b64_tr_b16 v[80:81], v1 offset:53472
	s_waitcnt lgkmcnt(0)
	v_mfma_f32_16x16x32_bf16 v[58:61], v[78:81], v[70:73], v[58:61]
	v_mfma_f32_16x16x32_bf16 v[54:57], v[78:81], v[74:77], v[54:57]
	ds_read_b64_tr_b16 v[78:79], v1 offset:52416
	ds_read_b64_tr_b16 v[80:81], v1 offset:53504
	s_waitcnt lgkmcnt(0)
	v_mfma_f32_16x16x32_bf16 v[66:69], v[78:81], v[70:73], v[66:69]
	v_mfma_f32_16x16x32_bf16 v[62:65], v[78:81], v[74:77], v[62:65]
	ds_read_b64_tr_b16 v[78:79], v1 offset:52448
	ds_read_b64_tr_b16 v[80:81], v1 offset:53536
	s_waitcnt lgkmcnt(0)
	v_mfma_f32_16x16x32_bf16 v[4:7], v[78:81], v[70:73], v[4:7]
	v_mfma_f32_16x16x32_bf16 v[10:13], v[78:81], v[74:77], v[10:13]
	ds_read_b64_tr_b16 v[70:71], v2 offset:26112
	ds_read_b64_tr_b16 v[72:73], v2 offset:27200
	ds_read_b64_tr_b16 v[74:75], v2 offset:26144
	ds_read_b64_tr_b16 v[76:77], v2 offset:27232
	ds_read_b64_tr_b16 v[78:79], v1 offset:60928
	ds_read_b64_tr_b16 v[80:81], v1 offset:62016
	s_waitcnt lgkmcnt(0)
	v_mfma_f32_16x16x32_bf16 v[22:25], v[78:81], v[70:73], v[22:25]
	v_mfma_f32_16x16x32_bf16 v[14:17], v[78:81], v[74:77], v[14:17]
	ds_read_b64_tr_b16 v[78:79], v1 offset:60960
	ds_read_b64_tr_b16 v[80:81], v1 offset:62048
	s_waitcnt lgkmcnt(0)
	v_mfma_f32_16x16x32_bf16 v[26:29], v[78:81], v[70:73], v[26:29]
	v_mfma_f32_16x16x32_bf16 v[18:21], v[78:81], v[74:77], v[18:21]
	ds_read_b64_tr_b16 v[78:79], v1 offset:60992
	ds_read_b64_tr_b16 v[80:81], v1 offset:62080
	s_waitcnt lgkmcnt(0)
	v_mfma_f32_16x16x32_bf16 v[34:37], v[78:81], v[70:73], v[34:37]
	v_mfma_f32_16x16x32_bf16 v[30:33], v[78:81], v[74:77], v[30:33]
	ds_read_b64_tr_b16 v[78:79], v1 offset:61024
	ds_read_b64_tr_b16 v[80:81], v1 offset:62112
	s_waitcnt lgkmcnt(0)
	v_mfma_f32_16x16x32_bf16 v[42:45], v[78:81], v[70:73], v[42:45]
	v_mfma_f32_16x16x32_bf16 v[38:41], v[78:81], v[74:77], v[38:41]
	ds_read_b64_tr_b16 v[78:79], v1 offset:61056
	ds_read_b64_tr_b16 v[80:81], v1 offset:62144
	s_waitcnt lgkmcnt(0)
	v_mfma_f32_16x16x32_bf16 v[50:53], v[78:81], v[70:73], v[50:53]
	v_mfma_f32_16x16x32_bf16 v[46:49], v[78:81], v[74:77], v[46:49]
	ds_read_b64_tr_b16 v[78:79], v1 offset:61088
	ds_read_b64_tr_b16 v[80:81], v1 offset:62176
	s_waitcnt lgkmcnt(0)
	v_mfma_f32_16x16x32_bf16 v[58:61], v[78:81], v[70:73], v[58:61]
	v_mfma_f32_16x16x32_bf16 v[54:57], v[78:81], v[74:77], v[54:57]
	ds_read_b64_tr_b16 v[78:79], v1 offset:61120
	ds_read_b64_tr_b16 v[80:81], v1 offset:62208
	s_waitcnt lgkmcnt(0)
	v_mfma_f32_16x16x32_bf16 v[66:69], v[78:81], v[70:73], v[66:69]
	v_mfma_f32_16x16x32_bf16 v[62:65], v[78:81], v[74:77], v[62:65]
	ds_read_b64_tr_b16 v[78:79], v1 offset:61152
	ds_read_b64_tr_b16 v[80:81], v1 offset:62240
	v_lshlrev_b32_e32 v1, 8, v8
	v_and_b32_e32 v1, 0xf00, v1
	v_lshl_or_b32 v208, s21, 13, v1
	s_waitcnt lgkmcnt(0)
	v_mfma_f32_16x16x32_bf16 v[2:5], v[78:81], v[70:73], v[4:7]
	v_mov_b32_e32 v1, v209
	s_nop 1
	v_lshl_add_u64 v[6:7], s[0:1], 0, v[208:209]
	v_lshl_add_u64 v[0:1], v[6:7], 0, v[0:1]
	v_cvt_pk_bf16_f32 v6, v22, v23
	v_cvt_pk_bf16_f32 v7, v24, v25
	global_store_dwordx2 v[0:1], v[6:7], off
	v_cvt_pk_bf16_f32 v6, v26, v27
	v_cvt_pk_bf16_f32 v7, v28, v29
	global_store_dwordx2 v[0:1], v[6:7], off offset:32
	v_cvt_pk_bf16_f32 v6, v34, v35
	v_cvt_pk_bf16_f32 v7, v36, v37
	global_store_dwordx2 v[0:1], v[6:7], off offset:64
	v_cvt_pk_bf16_f32 v6, v42, v43
	v_cvt_pk_bf16_f32 v7, v44, v45
	global_store_dwordx2 v[0:1], v[6:7], off offset:96
	v_cvt_pk_bf16_f32 v6, v50, v51
	v_cvt_pk_bf16_f32 v7, v52, v53
	global_store_dwordx2 v[0:1], v[6:7], off offset:128
	v_cvt_pk_bf16_f32 v6, v58, v59
	v_cvt_pk_bf16_f32 v7, v60, v61
	global_store_dwordx2 v[0:1], v[6:7], off offset:160
	v_cvt_pk_bf16_f32 v6, v66, v67
	v_cvt_pk_bf16_f32 v7, v68, v69
	v_cvt_pk_bf16_f32 v2, v2, v3
	v_cvt_pk_bf16_f32 v3, v4, v5
	s_movk_i32 s0, 0x1000
	global_store_dwordx2 v[0:1], v[6:7], off offset:192
	global_store_dwordx2 v[0:1], v[2:3], off offset:224
	v_add_co_u32_e32 v0, vcc, s0, v0
	v_cvt_pk_bf16_f32 v2, v14, v15
	v_cvt_pk_bf16_f32 v3, v16, v17
	v_addc_co_u32_e32 v1, vcc, 0, v1, vcc
	global_store_dwordx2 v[0:1], v[2:3], off
	v_cvt_pk_bf16_f32 v2, v18, v19
	v_cvt_pk_bf16_f32 v3, v20, v21
	global_store_dwordx2 v[0:1], v[2:3], off offset:32
	v_cvt_pk_bf16_f32 v2, v30, v31
	v_cvt_pk_bf16_f32 v3, v32, v33
	v_mfma_f32_16x16x32_bf16 v[10:13], v[78:81], v[74:77], v[10:13]
	global_store_dwordx2 v[0:1], v[2:3], off offset:64
	v_cvt_pk_bf16_f32 v2, v38, v39
	v_cvt_pk_bf16_f32 v3, v40, v41
	global_store_dwordx2 v[0:1], v[2:3], off offset:96
	v_cvt_pk_bf16_f32 v2, v46, v47
	v_cvt_pk_bf16_f32 v3, v48, v49
	global_store_dwordx2 v[0:1], v[2:3], off offset:128
	v_cvt_pk_bf16_f32 v2, v54, v55
	v_cvt_pk_bf16_f32 v3, v56, v57
	global_store_dwordx2 v[0:1], v[2:3], off offset:160
	v_cvt_pk_bf16_f32 v2, v62, v63
	v_cvt_pk_bf16_f32 v3, v64, v65
	global_store_dwordx2 v[0:1], v[2:3], off offset:192
	v_cvt_pk_bf16_f32 v2, v10, v11
	v_cvt_pk_bf16_f32 v3, v12, v13
	global_store_dwordx2 v[0:1], v[2:3], off offset:224
	s_barrier

.LBB0_457:
	s_andn2_b64 vcc, exec, s[0:1]
	s_cbranch_vccnz .LBB0_462
	v_mov_b32_e32 v0, v226
	s_add_i32 s20, s30, 0xffffff00
	s_mul_i32 s92, s20, 0x3c00
	v_ashrrev_i32_e32 v1, 31, v0
	v_lshlrev_b64 v[2:3], 2, v[0:1]
	v_lshl_add_u64 v[4:5], s[14:15], 0, v[2:3]
	s_lshl_b64 s[0:1], s[92:93], 2
	v_lshl_add_u64 v[12:13], v[4:5], 0, s[0:1]
	v_add_co_u32_e32 v14, vcc, 0x1000, v12
	s_movk_i32 s22, 0x2000
	s_nop 0
	v_addc_co_u32_e32 v15, vcc, 0, v13, vcc
	v_add_co_u32_e32 v16, vcc, s22, v12
	s_movk_i32 s35, 0x3000
	s_nop 0
	v_addc_co_u32_e32 v17, vcc, 0, v13, vcc
	v_add_co_u32_e32 v4, vcc, s35, v12
	s_movk_i32 s40, 0x5000
	s_nop 0
	v_addc_co_u32_e32 v5, vcc, 0, v13, vcc
	v_add_co_u32_e32 v18, vcc, s73, v12
	s_movk_i32 s23, 0x6000
	s_nop 0
	v_addc_co_u32_e32 v19, vcc, 0, v13, vcc
	v_add_co_u32_e32 v6, vcc, s40, v12
	s_movk_i32 s41, 0x7000
	s_nop 0
	v_addc_co_u32_e32 v7, vcc, 0, v13, vcc
	v_add_co_u32_e32 v20, vcc, s23, v12
	s_mov_b32 s42, 0x9000
	s_nop 0
	v_addc_co_u32_e32 v21, vcc, 0, v13, vcc
	v_add_co_u32_e32 v22, vcc, s41, v12
	s_mov_b32 s31, 0xa000
	s_nop 0
	v_addc_co_u32_e32 v23, vcc, 0, v13, vcc
	v_add_co_u32_e32 v24, vcc, s84, v12
	global_load_dword v11, v[4:5], off offset:-4096 nt
	global_load_dword v8, v[4:5], off nt
	global_load_dword v9, v[4:5], off offset:2048 nt
	global_load_dword v10, v[6:7], off offset:-4096 nt
	s_nop 0
	global_load_dword v5, v[6:7], off nt
	s_nop 0
	global_load_dword v6, v[6:7], off offset:2048 nt
	s_nop 0
	global_load_dword v7, v[22:23], off offset:-4096 nt
	global_load_dword v4, v[22:23], off nt
	v_addc_co_u32_e32 v25, vcc, 0, v13, vcc
	v_add_co_u32_e32 v26, vcc, s42, v12
	global_load_dword v34, v[12:13], off nt
	global_load_dword v35, v[12:13], off offset:2048 nt
	global_load_dword v36, v[14:15], off nt
	global_load_dword v37, v[14:15], off offset:2048 nt
	global_load_dword v38, v[16:17], off offset:2048 nt
	global_load_dword v39, v[18:19], off offset:2048 nt
	global_load_dword v40, v[20:21], off offset:2048 nt
	global_load_dword v41, v[24:25], off offset:2048 nt
	v_addc_co_u32_e32 v27, vcc, 0, v13, vcc
	v_add_co_u32_e32 v14, vcc, s31, v12
	s_mov_b32 s43, 0xb000
	s_nop 0
	v_addc_co_u32_e32 v15, vcc, 0, v13, vcc
	v_add_co_u32_e32 v16, vcc, s43, v12
	s_mov_b32 s70, 0xd000
	s_nop 0
	v_addc_co_u32_e32 v17, vcc, 0, v13, vcc
	v_add_co_u32_e32 v18, vcc, s75, v12
	s_mov_b32 s34, 0xe000
	s_nop 0
	v_addc_co_u32_e32 v19, vcc, 0, v13, vcc
	v_add_co_u32_e32 v20, vcc, s70, v12
	s_lshl_b32 s20, s20, 12
	s_nop 0
	v_addc_co_u32_e32 v21, vcc, 0, v13, vcc
	v_add_co_u32_e32 v12, vcc, s34, v12
	s_add_u32 s20, s88, s20
	s_nop 0
	v_addc_co_u32_e32 v13, vcc, 0, v13, vcc
	s_addc_u32 s21, s89, 0
	global_load_dword v42, v[22:23], off offset:2048 nt
	global_load_dword v43, v[26:27], off offset:-4096 nt
	global_load_dword v44, v[26:27], off nt
	global_load_dword v45, v[26:27], off offset:2048 nt
	global_load_dword v46, v[16:17], off offset:-4096 nt
	global_load_dword v47, v[16:17], off nt
	global_load_dword v48, v[16:17], off offset:2048 nt
	global_load_dword v49, v[20:21], off offset:-4096 nt
	global_load_dword v50, v[20:21], off nt
	global_load_dword v51, v[20:21], off offset:2048 nt
	global_load_dword v52, v[14:15], off offset:2048 nt
	global_load_dword v53, v[18:19], off offset:2048 nt
	global_load_dword v54, v[12:13], off nt
	global_load_dword v55, v[12:13], off offset:2048 nt
	v_lshl_add_u64 v[12:13], v[0:1], 1, s[20:21]
	s_mov_b32 s20, 0x1000000
	v_add_co_u32_e32 v12, vcc, s20, v12
	s_movk_i32 s21, 0x1000
	s_nop 0
	v_addc_co_u32_e32 v13, vcc, 0, v13, vcc
	global_load_ushort v1, v[12:13], off
	global_load_ushort v56, v[12:13], off offset:1024
	global_load_ushort v57, v[12:13], off offset:2048
	global_load_ushort v58, v[12:13], off offset:3072
	v_lshl_add_u64 v[12:13], s[4:5], 0, v[2:3]
	v_add_co_u32_e32 v14, vcc, s21, v12
	v_lshl_add_u64 v[32:33], s[6:7], 0, v[2:3]
	s_nop 0
	v_addc_co_u32_e32 v15, vcc, 0, v13, vcc
	v_add_co_u32_e32 v16, vcc, s22, v12
	global_load_dword v59, v[12:13], off
	global_load_dword v60, v[12:13], off offset:2048
	global_load_dword v61, v[14:15], off offset:2048
	v_addc_co_u32_e32 v17, vcc, 0, v13, vcc
	v_add_co_u32_e32 v14, vcc, s35, v12
	s_mov_b32 s20, 0xf000
	s_nop 0
	v_addc_co_u32_e32 v15, vcc, 0, v13, vcc
	v_add_co_u32_e32 v18, vcc, s73, v12
	v_lshl_add_u64 v[2:3], s[18:19], 0, v[2:3]
	s_nop 0
	v_addc_co_u32_e32 v19, vcc, 0, v13, vcc
	v_add_co_u32_e32 v20, vcc, s40, v12
	v_lshl_add_u64 v[2:3], v[2:3], 0, s[0:1]
	s_nop 0
	v_addc_co_u32_e32 v21, vcc, 0, v13, vcc
	v_add_co_u32_e32 v22, vcc, s23, v12
	v_addc_co_u32_e32 v23, vcc, 0, v13, vcc
	global_load_dword v62, v[16:17], off offset:-4096
	global_load_dword v63, v[16:17], off
	global_load_dword v64, v[16:17], off offset:2048
	global_load_dword v65, v[18:19], off offset:-4096
	global_load_dword v66, v[18:19], off
	global_load_dword v67, v[18:19], off offset:2048
	global_load_dword v68, v[22:23], off offset:-4096
	global_load_dword v69, v[22:23], off
	v_add_co_u32_e32 v16, vcc, s41, v12
	s_nop 1
	v_addc_co_u32_e32 v17, vcc, 0, v13, vcc
	v_add_co_u32_e32 v18, vcc, s84, v12
	s_nop 1
	v_addc_co_u32_e32 v19, vcc, 0, v13, vcc
	v_add_co_u32_e32 v24, vcc, s42, v12
	s_nop 1
	v_addc_co_u32_e32 v25, vcc, 0, v13, vcc
	v_add_co_u32_e32 v26, vcc, s31, v12
	s_nop 1
	v_addc_co_u32_e32 v27, vcc, 0, v13, vcc
	v_add_co_u32_e32 v28, vcc, s43, v12
	s_nop 1
	v_addc_co_u32_e32 v29, vcc, 0, v13, vcc
	v_add_co_u32_e32 v30, vcc, s75, v12
	s_nop 1
	v_addc_co_u32_e32 v31, vcc, 0, v13, vcc
	global_load_dword v32, v[32:33], off
	s_nop 0
	global_load_dword v22, v[22:23], off offset:2048
	s_nop 0
	global_load_dword v23, v[18:19], off offset:-4096
	global_load_dword v33, v[18:19], off
	s_nop 0
	global_load_dword v18, v[18:19], off offset:2048
	s_nop 0
	global_load_dword v19, v[26:27], off offset:-4096
	global_load_dword v70, v[26:27], off
	s_nop 0
	global_load_dword v26, v[26:27], off offset:2048
	s_nop 0
	global_load_dword v27, v[30:31], off offset:-4096
	global_load_dword v71, v[14:15], off offset:2048
	s_nop 0
	global_load_dword v20, v[20:21], off offset:2048
	s_nop 0
	global_load_dword v21, v[16:17], off offset:2048
	s_nop 0
	global_load_dword v24, v[24:25], off offset:2048
	s_nop 0
	global_load_dword v25, v[28:29], off offset:2048
	v_add_co_u32_e32 v14, vcc, s70, v12
	s_waitcnt vmcnt(13)
	v_lshlrev_b32_e32 v1, 16, v1
	v_fma_f32 v34, v34, v59, v32
	v_addc_co_u32_e32 v15, vcc, 0, v13, vcc
	v_add_co_u32_e32 v16, vcc, s34, v12
	v_fmac_f32_e32 v34, v35, v60
	s_nop 0
	v_addc_co_u32_e32 v17, vcc, 0, v13, vcc
	global_load_dword v14, v[14:15], off offset:2048
	s_nop 0
	global_load_dword v15, v[30:31], off
	global_load_dword v28, v[30:31], off offset:2048
	global_load_dword v29, v[16:17], off offset:-4096
	s_nop 0
	global_load_dword v30, v[16:17], off
	s_nop 0
	global_load_dword v16, v[16:17], off offset:2048
	v_add_co_u32_e32 v12, vcc, s20, v12
	v_fma_f32 v35, v35, v59, v32
	s_nop 0
	v_addc_co_u32_e32 v13, vcc, 0, v13, vcc
	global_load_dword v12, v[12:13], off
	v_fmac_f32_e32 v35, v36, v60
	v_fmac_f32_e32 v34, v36, v62
	v_fmac_f32_e32 v35, v37, v62
	v_fmac_f32_e32 v34, v37, v61
	v_fmac_f32_e32 v35, v11, v61
	v_fmac_f32_e32 v34, v11, v63
	v_fmac_f32_e32 v35, v38, v63
	v_fmac_f32_e32 v34, v38, v64
	v_fmac_f32_e32 v35, v8, v64
	v_fmac_f32_e32 v34, v8, v65
	v_fmac_f32_e32 v35, v9, v65
	s_waitcnt vmcnt(11)
	v_fmac_f32_e32 v34, v9, v71
	v_fmac_f32_e32 v35, v10, v71
	v_fmac_f32_e32 v34, v10, v66
	v_fmac_f32_e32 v35, v39, v66
	v_fmac_f32_e32 v34, v39, v67
	v_fmac_f32_e32 v35, v5, v67
	v_fmac_f32_e32 v34, v5, v68
	v_fmac_f32_e32 v35, v6, v68
	s_waitcnt vmcnt(10)
	v_fmac_f32_e32 v34, v6, v20
	v_fmac_f32_e32 v35, v7, v20
	v_fmac_f32_e32 v34, v7, v69
	v_fmac_f32_e32 v35, v40, v69
	v_fmac_f32_e32 v34, v40, v22
	v_fmac_f32_e32 v35, v4, v22
	v_fmac_f32_e32 v34, v4, v23
	v_fmac_f32_e32 v35, v42, v23
	s_waitcnt vmcnt(9)
	v_fmac_f32_e32 v34, v42, v21
	v_fmac_f32_e32 v35, v43, v21
	v_fmac_f32_e32 v34, v43, v33
	v_fmac_f32_e32 v35, v41, v33
	v_fmac_f32_e32 v34, v41, v18
	v_fmac_f32_e32 v35, v44, v18
	v_fmac_f32_e32 v34, v44, v19
	v_fmac_f32_e32 v35, v45, v19
	s_waitcnt vmcnt(8)
	v_fmac_f32_e32 v34, v45, v24
	v_fmac_f32_e32 v35, v46, v24
	v_fmac_f32_e32 v34, v46, v70
	v_fmac_f32_e32 v35, v52, v70
	v_fmac_f32_e32 v34, v52, v26
	v_fmac_f32_e32 v35, v47, v26
	v_fmac_f32_e32 v34, v47, v27
	v_fmac_f32_e32 v35, v48, v27
	s_waitcnt vmcnt(7)
	v_fmac_f32_e32 v34, v48, v25
	v_fmac_f32_e32 v35, v49, v25
	v_lshlrev_b32_e32 v17, 16, v56
	v_lshl_add_u32 v13, v0, 2, 0
	v_lshlrev_b32_e32 v31, 16, v57
	v_lshlrev_b32_e32 v56, 16, v58
	v_readfirstlane_b32 s20, v0
	s_ashr_i32 s1, s20, 6
	s_cmp_gt_i32 s1, 3
	s_waitcnt vmcnt(5)
	v_fmac_f32_e32 v34, v49, v15
	v_fmac_f32_e32 v35, v53, v15
	s_waitcnt vmcnt(4)
	v_fmac_f32_e32 v34, v53, v28
	v_fmac_f32_e32 v35, v50, v28
	s_waitcnt vmcnt(3)
	v_fmac_f32_e32 v34, v50, v29
	v_fmac_f32_e32 v35, v51, v29
	v_fmac_f32_e32 v34, v51, v14
	v_fmac_f32_e32 v35, v54, v14
	s_waitcnt vmcnt(2)
	v_fmac_f32_e32 v34, v54, v30
	v_fmac_f32_e32 v35, v55, v30
	s_waitcnt vmcnt(1)
	v_fmac_f32_e32 v34, v55, v16
	v_fmac_f32_e32 v35, v16, v1
	s_waitcnt vmcnt(0)
	v_fmac_f32_e32 v34, v12, v1
	v_fmac_f32_e32 v35, v12, v17
	ds_write2st64_b32 v13, v34, v35 offset1:8
	v_fma_f32 v34, v36, v59, v32
	v_fmac_f32_e32 v32, v37, v59
	v_fmac_f32_e32 v34, v37, v60
	v_fmac_f32_e32 v32, v11, v60
	v_fmac_f32_e32 v34, v11, v62
	v_fmac_f32_e32 v32, v38, v62
	v_fmac_f32_e32 v34, v38, v61
	v_fmac_f32_e32 v32, v8, v61
	v_fmac_f32_e32 v34, v8, v63
	v_fmac_f32_e32 v32, v9, v63
	v_fmac_f32_e32 v34, v9, v64
	v_fmac_f32_e32 v32, v10, v64
	v_fmac_f32_e32 v34, v10, v65
	v_fmac_f32_e32 v32, v39, v65
	v_fmac_f32_e32 v34, v39, v71
	v_fmac_f32_e32 v32, v5, v71
	v_fmac_f32_e32 v34, v5, v66
	v_fmac_f32_e32 v32, v6, v66
	v_fmac_f32_e32 v34, v6, v67
	v_fmac_f32_e32 v32, v7, v67
	v_fmac_f32_e32 v34, v7, v68
	v_fmac_f32_e32 v32, v40, v68
	v_fmac_f32_e32 v34, v40, v20
	v_fmac_f32_e32 v32, v4, v20
	v_fmac_f32_e32 v34, v4, v69
	v_fmac_f32_e32 v32, v42, v69
	v_fmac_f32_e32 v34, v42, v22
	v_fmac_f32_e32 v32, v43, v22
	v_fmac_f32_e32 v34, v43, v23
	v_fmac_f32_e32 v32, v41, v23
	v_fmac_f32_e32 v34, v41, v21
	v_fmac_f32_e32 v32, v44, v21
	v_fmac_f32_e32 v34, v44, v33
	v_fmac_f32_e32 v32, v45, v33
	v_fmac_f32_e32 v34, v45, v18
	v_fmac_f32_e32 v32, v46, v18
	v_fmac_f32_e32 v34, v46, v19
	v_fmac_f32_e32 v32, v52, v19
	v_fmac_f32_e32 v34, v52, v24
	v_fmac_f32_e32 v32, v47, v24
	v_fmac_f32_e32 v34, v47, v70
	v_fmac_f32_e32 v32, v48, v70
	v_fmac_f32_e32 v34, v48, v26
	v_fmac_f32_e32 v32, v49, v26
	v_fmac_f32_e32 v34, v49, v27
	v_fmac_f32_e32 v32, v53, v27
	v_fmac_f32_e32 v34, v53, v25
	v_fmac_f32_e32 v32, v50, v25
	v_fmac_f32_e32 v34, v50, v15
	v_fmac_f32_e32 v32, v51, v15
	v_fmac_f32_e32 v34, v51, v28
	v_fmac_f32_e32 v32, v54, v28
	v_fmac_f32_e32 v34, v54, v29
	v_fmac_f32_e32 v32, v55, v29
	v_fmac_f32_e32 v34, v55, v14
	v_fmac_f32_e32 v32, v14, v1
	v_fmac_f32_e32 v34, v30, v1
	v_fmac_f32_e32 v32, v30, v17
	v_fmac_f32_e32 v34, v16, v17
	v_fmac_f32_e32 v32, v16, v31
	v_fmac_f32_e32 v34, v12, v31
	v_fmac_f32_e32 v32, v12, v56
	v_add_co_u32_e32 v12, vcc, s21, v2
	ds_write2st64_b32 v13, v34, v32 offset0:16 offset1:24
	s_nop 0
	v_addc_co_u32_e32 v13, vcc, 0, v3, vcc
	v_add_co_u32_e32 v14, vcc, s22, v2
	global_store_dword v[2:3], v11, off nt
	global_store_dword v[2:3], v38, off offset:2048 nt
	v_addc_co_u32_e32 v15, vcc, 0, v3, vcc
	global_store_dword v[14:15], v8, off offset:-4096 nt
	global_store_dword v[12:13], v9, off offset:2048 nt
	global_store_dword v[14:15], v10, off nt
	global_store_dword v[14:15], v39, off offset:2048 nt
	v_add_co_u32_e32 v8, vcc, s35, v2
	s_nop 1
	v_addc_co_u32_e32 v9, vcc, 0, v3, vcc
	v_add_co_u32_e32 v10, vcc, s73, v2
	s_nop 1
	v_addc_co_u32_e32 v11, vcc, 0, v3, vcc
	global_store_dword v[10:11], v5, off offset:-4096 nt
	global_store_dword v[8:9], v6, off offset:2048 nt
	global_store_dword v[10:11], v7, off nt
	global_store_dword v[10:11], v40, off offset:2048 nt
	v_add_co_u32_e32 v6, vcc, s40, v2
	s_nop 1
	v_addc_co_u32_e32 v7, vcc, 0, v3, vcc
	v_add_co_u32_e32 v8, vcc, s23, v2
	s_nop 1
	v_addc_co_u32_e32 v9, vcc, 0, v3, vcc
	global_store_dword v[8:9], v4, off offset:-4096 nt
	global_store_dword v[6:7], v42, off offset:2048 nt
	global_store_dword v[8:9], v43, off nt
	global_store_dword v[8:9], v41, off offset:2048 nt
	v_add_co_u32_e32 v4, vcc, s41, v2
	s_nop 1
	v_addc_co_u32_e32 v5, vcc, 0, v3, vcc
	v_add_co_u32_e32 v6, vcc, s84, v2
	s_nop 1
	v_addc_co_u32_e32 v7, vcc, 0, v3, vcc
	global_store_dword v[6:7], v44, off offset:-4096 nt
	global_store_dword v[4:5], v45, off offset:2048 nt
	global_store_dword v[6:7], v46, off nt
	global_store_dword v[6:7], v52, off offset:2048 nt
	v_add_co_u32_e32 v4, vcc, s42, v2
	s_nop 1
	v_addc_co_u32_e32 v5, vcc, 0, v3, vcc
	v_add_co_u32_e32 v6, vcc, s31, v2
	s_nop 1
	v_addc_co_u32_e32 v7, vcc, 0, v3, vcc
	global_store_dword v[6:7], v47, off offset:-4096 nt
	global_store_dword v[4:5], v48, off offset:2048 nt
	global_store_dword v[6:7], v49, off nt
	global_store_dword v[6:7], v53, off offset:2048 nt
	v_add_co_u32_e32 v4, vcc, 0xb000, v2
	s_nop 1
	v_addc_co_u32_e32 v5, vcc, 0, v3, vcc
	global_store_dword v[4:5], v50, off nt
	global_store_dword v[4:5], v51, off offset:2048 nt
	v_add_co_u32_e32 v4, vcc, s75, v2
	s_nop 1
	v_addc_co_u32_e32 v5, vcc, 0, v3, vcc
	global_store_dword v[4:5], v54, off nt
	global_store_dword v[4:5], v55, off offset:2048 nt
	v_add_co_u32_e32 v4, vcc, 0xd000, v2
	s_nop 1
	v_addc_co_u32_e32 v5, vcc, 0, v3, vcc
	v_add_co_u32_e32 v2, vcc, 0xe000, v2
	global_store_dword v[4:5], v1, off nt
	global_store_dword v[4:5], v17, off offset:2048 nt
	v_addc_co_u32_e32 v3, vcc, 0, v3, vcc
	global_store_dword v[2:3], v31, off nt
	global_store_dword v[2:3], v56, off offset:2048 nt
	s_waitcnt lgkmcnt(0)
	s_barrier
	s_cbranch_scc1 .LBB0_461
	v_and_b32_e32 v1, 64, v230
	v_add_u32_e32 v1, 64, v1
	v_xor_b32_e32 v2, 1, v230
	v_cmp_lt_i32_e32 vcc, v2, v1
	s_lshl_b32 s20, s1, 11
	s_add_i32 s0, s1, -8
	v_cndmask_b32_e32 v2, v230, v2, vcc
	v_lshlrev_b32_e32 v15, 2, v2
	v_xor_b32_e32 v2, 2, v230
	v_cmp_lt_i32_e32 vcc, v2, v1
	s_add_i32 s20, s20, 0
	s_ashr_i32 s21, s1, 31
	v_cndmask_b32_e32 v2, v230, v2, vcc
	v_lshlrev_b32_e32 v16, 2, v2
	v_xor_b32_e32 v2, 4, v230
	v_cmp_lt_i32_e32 vcc, v2, v1
	s_nop 1
	v_cndmask_b32_e32 v2, v230, v2, vcc
	v_lshlrev_b32_e32 v17, 2, v2
	v_xor_b32_e32 v2, 8, v230
	v_cmp_lt_i32_e32 vcc, v2, v1
	s_nop 1
	v_cndmask_b32_e32 v2, v230, v2, vcc
	v_lshlrev_b32_e32 v18, 2, v2
	v_xor_b32_e32 v2, 16, v230
	v_cmp_lt_i32_e32 vcc, v2, v1
	s_nop 1
	v_cndmask_b32_e32 v2, v230, v2, vcc
	v_lshlrev_b32_e32 v19, 2, v2
	v_xor_b32_e32 v2, 32, v230
	v_cmp_lt_i32_e32 vcc, v2, v1
	s_nop 1
	v_cndmask_b32_e32 v1, v230, v2, vcc
	v_lshlrev_b32_e32 v20, 2, v1
	v_lshlrev_b32_e32 v1, 5, v0
	v_and_b32_e32 v0, 63, v0
	v_lshl_add_u32 v21, v0, 5, s20
	s_add_u32 s20, s1, s29
	s_addc_u32 s21, s21, 0
	s_lshl_b64 s[20:21], s[20:21], 11
	v_and_b32_e32 v208, 0x7e0, v1
	s_add_u32 s20, s86, s20
	v_lshl_add_u64 v[8:9], s[10:11], 0, v[208:209]
	v_lshl_add_u64 v[10:11], s[12:13], 0, v[208:209]
	v_lshlrev_b32_e32 v208, 4, v0
	s_addc_u32 s21, s87, s21
	v_lshl_add_u64 v[12:13], s[20:21], 0, v[208:209]
